# GLA chunk-state scan spread over all 256 workgroups (waves 4-7), concurrent with the S5 scan on waves 0-1
# speedup vs baseline: 1.0093x; 1.0056x over previous
; __device__ __forceinline__ int otid() { int t = threadIdx.x; asm volatile("" : "+v"(t)); return t; }
; __device__ __forceinline__ int obid() { int t = blockIdx.x; asm volatile("" : "+s"(t)); return t; }
; __device__ void phase_gla_b(CP P) {
;     bf16_t* GST = (bf16_t*)(P->ws + OFF_GST); const float* GDEC = (const float*)(P->ws + OFF_GDEC);
;     for (int idx = obid() * NTHR + otid(); idx < 64 * 1024; idx += gridDim.x * NTHR) {
;         const int bhd = idx >> 10, e = (idx & 1023) * 8, d = e >> 7, dir = bhd & 1;
.LBB0_160:
	s_or_b64 exec, exec, s[36:37]
	s_mov_b32 s10, s2
	v_mov_b32_e32 v0, v191
	s_nop 0
	v_add_u32_e32 v1, 0xffffff00, v0
	v_lshl_add_u32 v45, s10, 8, v1
	v_cmp_gt_i32_e32 vcc, s54, v45
	s_mov_b64 s[38:39], vcc
	v_cmp_lt_u32_e32 vcc, 0xff, v0
	s_and_b64 vcc, vcc, s[38:39]
	s_and_saveexec_b64 s[36:37], vcc
	s_cbranch_execz .LBB0_165
	s_load_dword s10, s[86:87], 0x0
	s_mov_b64 s[38:39], 0
	s_waitcnt lgkmcnt(0)
	s_lshl_b32 s10, s10, 8
